# v20 plus: non-leader workgroups poll the top-level barrier generation word directly (one relay hop less per grid barrier)
# baseline (speedup 1.0000x reference)
; __device__ __forceinline__ unsigned xb_ld(unsigned* p)              { return __hip_atomic_load(p, __ATOMIC_RELAXED, __HIP_MEMORY_SCOPE_AGENT); }
; __device__ __forceinline__ unsigned xb_add(unsigned* p, unsigned v) { return __hip_atomic_fetch_add(p, v, __ATOMIC_RELAXED, __HIP_MEMORY_SCOPE_AGENT); }
; #define XB_SPIN(cond, bar) do { unsigned _sp = 0; while (cond) { __builtin_amdgcn_s_sleep(1); \
;     if ((++_sp & 255u) == 0u) { if (xb_ld(&(bar)[XB_TMO])) break; if (_sp > XB_SPIN_CAP) { atomicAdd(&(bar)[XB_TMO], 1u); break; } } } } while (0)
; __device__ __forceinline__ void xcd_barrier(const XcdBarrier& b) {
;     ...
;         const unsigned old = xb_add(&bar[XB_XSUB(b.x)], 1u);
;         const unsigned gen = old / nloc;
;         if (old + 1u == (gen + 1u) * nloc) {
;             __builtin_amdgcn_fence(__ATOMIC_RELEASE, "agent");
;             asm volatile("s_waitcnt vmcnt(0)" ::: "memory");
;             const unsigned og = xb_add(&bar[XB_TOP], 1u);
;             const unsigned tg = og / nx;
;             if (og + 1u == (tg + 1u) * nx) xb_add(&bar[XB_TOPGEN], 1u);
;             else XB_SPIN(xb_ld(&bar[XB_TOPGEN]) == tg, bar);
;             __builtin_amdgcn_fence(__ATOMIC_ACQUIRE, "agent");
;             xb_add(&bar[XB_XGEN(b.x)], 1u);
;             asm volatile("s_waitcnt vmcnt(0)" ::: "memory");
;         } else {
;             XB_SPIN(xb_ld(&bar[XB_XGEN(b.x)]) == gen, bar);
.LBB0_70:
	s_or_b64 exec, exec, s[12:13]
	v_cvt_f32_u32_e32 v4, v2
	s_waitcnt vmcnt(0)
	v_readfirstlane_b32 s6, v3
	v_sub_u32_e32 v3, 0, v2
	v_rcp_iflag_f32_e32 v4, v4
	v_add_u32_e32 v5, s6, v1
	v_mul_f32_e32 v4, 0x4f7ffffe, v4
	v_cvt_u32_f32_e32 v4, v4
	v_mul_lo_u32 v1, v3, v4
	v_mul_hi_u32 v1, v4, v1
	v_add_u32_e32 v1, v4, v1
	v_mul_hi_u32 v1, v5, v1
	v_mul_lo_u32 v3, v1, v2
	v_sub_u32_e32 v3, v5, v3
	v_add_u32_e32 v4, 1, v1
	v_cmp_ge_u32_e32 vcc, v3, v2
	s_nop 1
	v_cndmask_b32_e32 v1, v1, v4, vcc
	v_sub_u32_e32 v4, v3, v2
	v_cndmask_b32_e32 v3, v3, v4, vcc
	v_add_u32_e32 v4, 1, v1
	v_cmp_ge_u32_e32 vcc, v3, v2
	v_add_u32_e32 v3, 1, v5
	s_nop 0
	v_cndmask_b32_e32 v1, v1, v4, vcc
	v_mul_lo_u32 v4, v2, v1
	v_add_u32_e32 v2, v4, v2
	v_cmp_ne_u32_e32 vcc, v3, v2
	s_and_saveexec_b64 s[6:7], vcc
	s_xor_b64 s[12:13], exec, s[6:7]
	s_cbranch_execz .LBB0_84
	s_waitcnt lgkmcnt(0)
	v_mov_b32_e32 v0, 0x1de03500
	buffer_inv sc1
	global_load_dword v0, v0, s[62:63] sc1
	s_add_u32 s18, s62, 0x1de03500
	s_addc_u32 s19, s63, 0
	s_waitcnt vmcnt(0)
	v_cmp_eq_u32_e32 vcc, v0, v1
	s_and_saveexec_b64 s[14:15], vcc
	s_cbranch_execz .LBB0_83
	s_add_u32 s16, s62, 0x1de00200
	s_addc_u32 s17, s63, 0
	s_mov_b32 s6, 1
	s_mov_b64 s[20:21], 0
	v_mov_b32_e32 v0, 0
	s_branch .LBB0_74

; __device__ __forceinline__ unsigned xb_ld(unsigned* p)              { return __hip_atomic_load(p, __ATOMIC_RELAXED, __HIP_MEMORY_SCOPE_AGENT); }
; __device__ __forceinline__ unsigned xb_add(unsigned* p, unsigned v) { return __hip_atomic_fetch_add(p, v, __ATOMIC_RELAXED, __HIP_MEMORY_SCOPE_AGENT); }
; #define XB_SPIN(cond, bar) do { unsigned _sp = 0; while (cond) { __builtin_amdgcn_s_sleep(1); \
;     if ((++_sp & 255u) == 0u) { if (xb_ld(&(bar)[XB_TMO])) break; if (_sp > XB_SPIN_CAP) { atomicAdd(&(bar)[XB_TMO], 1u); break; } } } } while (0)
; __device__ __forceinline__ void xcd_barrier(const XcdBarrier& b) {
;     ...
;         const unsigned old = xb_add(&bar[XB_XSUB(b.x)], 1u);
;         const unsigned gen = old / nloc;
;         if (old + 1u == (gen + 1u) * nloc) {
;             __builtin_amdgcn_fence(__ATOMIC_RELEASE, "agent");
;             asm volatile("s_waitcnt vmcnt(0)" ::: "memory");
;             const unsigned og = xb_add(&bar[XB_TOP], 1u);
;             const unsigned tg = og / nx;
;             if (og + 1u == (tg + 1u) * nx) xb_add(&bar[XB_TOPGEN], 1u);
;             else XB_SPIN(xb_ld(&bar[XB_TOPGEN]) == tg, bar);
;             __builtin_amdgcn_fence(__ATOMIC_ACQUIRE, "agent");
;             xb_add(&bar[XB_XGEN(b.x)], 1u);
;             asm volatile("s_waitcnt vmcnt(0)" ::: "memory");
;         } else {
;             XB_SPIN(xb_ld(&bar[XB_XGEN(b.x)]) == gen, bar);
.LBB0_459:
	s_or_b64 exec, exec, s[10:11]
	v_cvt_f32_u32_e32 v4, v2
	s_waitcnt vmcnt(0)
	v_readfirstlane_b32 s8, v3
	v_sub_u32_e32 v3, 0, v2
	v_rcp_iflag_f32_e32 v4, v4
	v_add_u32_e32 v5, s8, v1
	v_mul_f32_e32 v4, 0x4f7ffffe, v4
	v_cvt_u32_f32_e32 v4, v4
	v_mul_lo_u32 v1, v3, v4
	v_mul_hi_u32 v1, v4, v1
	v_add_u32_e32 v1, v4, v1
	v_mul_hi_u32 v1, v5, v1
	v_mul_lo_u32 v3, v1, v2
	v_sub_u32_e32 v3, v5, v3
	v_add_u32_e32 v4, 1, v1
	v_cmp_ge_u32_e32 vcc, v3, v2
	s_nop 1
	v_cndmask_b32_e32 v1, v1, v4, vcc
	v_sub_u32_e32 v4, v3, v2
	v_cndmask_b32_e32 v3, v3, v4, vcc
	v_add_u32_e32 v4, 1, v1
	v_cmp_ge_u32_e32 vcc, v3, v2
	v_add_u32_e32 v3, 1, v5
	s_nop 0
	v_cndmask_b32_e32 v1, v1, v4, vcc
	v_mul_lo_u32 v4, v2, v1
	v_add_u32_e32 v2, v4, v2
	v_cmp_ne_u32_e32 vcc, v3, v2
	s_and_saveexec_b64 s[8:9], vcc
	s_xor_b64 s[8:9], exec, s[8:9]
	s_cbranch_execz .LBB0_473
	s_waitcnt lgkmcnt(0)
	v_mov_b32_e32 v0, 0x1de03500
	buffer_inv sc1
	global_load_dword v0, v0, s[62:63] sc1
	s_add_u32 s14, s62, 0x1de03500
	s_addc_u32 s15, s63, 0
	s_waitcnt vmcnt(0)
	v_cmp_eq_u32_e32 vcc, v0, v1
	s_and_saveexec_b64 s[10:11], vcc
	s_cbranch_execz .LBB0_472
	s_add_u32 s12, s62, 0x1de00200
	s_addc_u32 s13, s63, 0
	s_mov_b32 s26, 1
	s_mov_b64 s[16:17], 0
	v_mov_b32_e32 v0, 0
	s_branch .LBB0_463
